# dilated attention: q-tile loads marked nt (read once per item)
# baseline (speedup 1.0000x reference)
.LBB0_1110:
	s_add_i32 s44, s78, s33
	s_ashr_i32 s70, s44, 11
	s_bfe_u32 s90, s44, 0x30006
	s_and_b32 s44, s44, 63
	s_lshl_b32 s89, s70, 1
	s_lshr_b32 s92, s44, s89
	s_bfm_b32 s45, s89, 0
	s_lshl_b32 s91, s92, 7
	s_and_b32 s46, s45, s44
	s_or_b32 s54, s91, s80
	s_and_b32 s47, s84, 0x6000
	s_lshl_b64 s[44:45], s[54:55], s89
	s_or_b32 s46, s46, s47
	s_add_u32 s56, s44, s46
	s_addc_u32 s57, s45, 0
	s_mul_i32 s44, s57, 0x1400
	s_mul_hi_u32 s45, s56, 0x1400
	s_add_i32 s45, s45, s44
	s_mul_i32 s44, s56, 0x1400
	s_add_u32 s44, s76, s44
	s_addc_u32 s45, s77, s45
	s_lshl_b32 s46, s90, 7
	s_add_u32 s44, s44, s46
	s_addc_u32 s45, s45, 0
	s_lshl_b64 s[46:47], 0xa00, s89
	v_mad_u64_u32 v[0:1], s[58:59], s46, v162, 0
	v_mov_b32_e32 v2, v1
	v_mad_u64_u32 v[2:3], s[46:47], s47, v162, v[2:3]
	v_mov_b32_e32 v1, v2
	v_lshl_add_u64 v[0:1], v[0:1], 1, s[44:45]
	v_lshl_add_u64 v[0:1], v[0:1], 0, v[160:161]
	global_load_dwordx4 v[156:159], v[0:1], off nt
	global_load_dwordx4 v[152:155], v[0:1], off offset:32 nt
	global_load_dwordx4 v[148:151], v[0:1], off offset:64 nt
	global_load_dwordx4 v[144:147], v[0:1], off offset:96 nt
	s_barrier
	s_waitcnt vmcnt(4)
	ds_write_b128 v179, v[80:83]
	s_waitcnt vmcnt(4)
	ds_write_b128 v180, v[84:87] offset:36864
	ds_write_b128 v179, v[92:95] offset:4608
	ds_write_b128 v182, v[88:91] offset:36864
	ds_write_b128 v179, v[100:103] offset:9216
	ds_write_b128 v184, v[96:99] offset:36864
	ds_write_b128 v179, v[104:107] offset:13824
	ds_write_b128 v185, v[108:111] offset:36864
	s_waitcnt vmcnt(4)
	ds_write_b128 v179, v[112:115] offset:18432
	s_waitcnt vmcnt(4)
	ds_write_b128 v186, v[128:131] offset:36864
	ds_write_b128 v179, v[120:123] offset:23040
	ds_write_b128 v187, v[132:135] offset:36864
	ds_write_b128 v179, v[124:127] offset:27648
	ds_write_b128 v188, v[136:139] offset:36864
	ds_write_b128 v179, v[140:143] offset:32256
	ds_write_b128 v189, v[116:119] offset:36864
	s_waitcnt lgkmcnt(0)
	s_barrier
	s_waitcnt vmcnt(0)
	s_add_i32 s88, s88, s66
	s_cmpk_gt_i32 s88, 0xbff
	s_cselect_b64 s[58:59], -1, 0
	s_and_b64 vcc, exec, s[58:59]
	s_cbranch_vccnz .LBB0_1118
	s_add_i32 s44, s82, s33
	s_bfe_u32 s45, s44, 0x20009
	s_and_b32 s95, s44, 0x1c0
	s_and_b32 s46, s44, 63
	s_ashr_i32 s44, s44, 10
	s_and_b32 s71, s44, -2
	s_lshr_b32 vcc_lo, s46, s71
	s_bfm_b32 s44, s71, 0
	s_lshl_b32 s94, vcc_lo, 7
	s_and_b32 s93, s44, s46
	s_addk_i32 s94, 0xff80
	s_mul_i32 s44, s45, 0x2800000
	s_mov_b32 s45, s55
	s_cmp_lg_u32 vcc_lo, 0
	v_lshl_add_u64 v[0:1], v[164:165], 0, s[44:45]
	s_cselect_b64 s[46:47], -1, 0
	s_cmp_eq_u32 vcc_lo, 0
	s_cbranch_scc1 .LBB0_1124
	v_or_b32_e32 v2, s94, v167
	v_lshlrev_b32_e32 v2, s71, v2
	v_add_u32_e32 v2, s93, v2
	v_mad_i64_i32 v[2:3], s[44:45], v2, s79, v[0:1]
	s_lshl_b32 s44, s95, 1
	s_mov_b32 s45, s55
	v_lshl_add_u64 v[2:3], v[2:3], 0, s[44:45]
	global_load_dwordx4 v[80:83], v[2:3], off offset:1024
	global_load_dwordx4 v[84:87], v[2:3], off offset:2048
	v_cndmask_b32_e64 v2, 0, 1, s[46:47]
	v_cmp_ne_u32_e64 s[44:45], 1, v2
	s_andn2_b64 vcc, exec, s[46:47]
	s_cbranch_vccnz .LBB0_1125
